# v27 + rwkv_prep key-mix section: the three later current/previous row load pairs issued together with the first pair (one load round trip instead of four)
# speedup vs baseline: 1.0050x; 1.0004x over previous
; DI void rwkv_prep_item(KA a, const int l, LAS unsigned char* lds, const int tile) {
;     ...
;     for (int rt = 0; rt < 2; ++rt) { const int tk = t0 + 32 * th + 16 * rt + fr; const bool first = (tk & (SEQ - 1)) == 0;
; #pragma unroll
;         for (int ct = 0; ct < 4; ++ct) { const int c4 = hd * 64 + ct * 16 + 4 * fq; const f32x4 muk = *(const f32x4*)(mu + 256 + c4), kk4 = *(const f32x4*)(kkw + c4);
;             const bf16* hp = H + (size_t)tk * HP + C_RK + c4; const v2u cu = *(const v2u*)hp; v2u pv = {0u, 0u}; if (!first) pv = *(const v2u*)(hp - HP);
;             const float c_[4] = {bflo(cu.x), bfhi(cu.x), bflo(cu.y), bfhi(cu.y)}, p_[4] = {bflo(pv.x), bfhi(pv.x), bflo(pv.y), bfhi(pv.y)};
; #pragma unroll
;             for (int j = 0; j < 4; ++j) { const float k = c_[j] + (p_[j] - c_[j]) * muk[j]; kx[rt][ct][j] = k; const float kk = k * kk4[j]; ss[rt] += kk * kk; } } }
.LBB0_348:
	s_or_b64 exec, exec, s[54:55]
	s_waitcnt vmcnt(9)
	v_lshlrev_b32_e32 v184, 16, v142
	v_and_b32_e32 v186, 0xffff0000, v142
	v_lshlrev_b32_e32 v135, 16, v150
	v_and_b32_e32 v142, 0xffff0000, v150
	v_lshlrev_b32_e32 v188, 16, v143
	v_and_b32_e32 v182, 0xffff0000, v143
	v_lshlrev_b32_e32 v143, 16, v151
	v_sub_f32_e32 v135, v135, v184
	v_sub_f32_e32 v142, v142, v186
	v_and_b32_e32 v150, 0xffff0000, v151
	v_fmac_f32_e32 v184, v120, v135
	v_fmac_f32_e32 v186, v121, v142
	v_sub_f32_e32 v142, v143, v188
	v_mul_f32_e32 v185, v124, v184
	v_fmac_f32_e32 v188, v122, v142
	v_sub_f32_e32 v142, v150, v182
	v_mul_f32_e32 v135, v185, v185
	v_mul_f32_e32 v187, v125, v186
	v_fmac_f32_e32 v182, v123, v142
	s_waitcnt vmcnt(6)
	v_lshlrev_b32_e32 v179, 16, v144
	v_lshlrev_b32_e32 v142, 16, v138
	v_fmac_f32_e32 v135, v187, v187
	v_mul_f32_e32 v191, v126, v188
	v_and_b32_e32 v180, 0xffff0000, v144
	v_and_b32_e32 v138, 0xffff0000, v138
	v_sub_f32_e32 v142, v142, v179
	v_fmac_f32_e32 v135, v191, v191
	v_mul_f32_e32 v183, v127, v182
	v_fmac_f32_e32 v179, v112, v142
	v_sub_f32_e32 v138, v138, v180
	v_fmac_f32_e32 v135, v183, v183
	v_mul_f32_e32 v142, v116, v179
	v_fmac_f32_e32 v180, v113, v138
	v_lshlrev_b32_e32 v181, 16, v145
	v_lshlrev_b32_e32 v143, 16, v139
	v_fmac_f32_e32 v135, v142, v142
	v_mul_f32_e32 v138, v117, v180
	v_fmac_f32_e32 v135, v138, v138
	v_sub_f32_e32 v138, v143, v181
	v_fmac_f32_e32 v181, v114, v138
	v_and_b32_e32 v178, 0xffff0000, v145
	v_and_b32_e32 v139, 0xffff0000, v139
	v_mul_f32_e32 v138, v118, v181
	v_fmac_f32_e32 v135, v138, v138
	v_sub_f32_e32 v138, v139, v178
	v_fmac_f32_e32 v178, v115, v138
	v_mul_f32_e32 v138, v119, v178
	v_fmac_f32_e32 v135, v138, v138
	s_waitcnt vmcnt(3)
	v_lshlrev_b32_e32 v175, 16, v146
	v_lshlrev_b32_e32 v138, 16, v152
	v_sub_f32_e32 v138, v138, v175
	v_fmac_f32_e32 v175, v104, v138
	v_and_b32_e32 v176, 0xffff0000, v146
	v_and_b32_e32 v139, 0xffff0000, v152
	v_mul_f32_e32 v138, v108, v175
	v_fmac_f32_e32 v135, v138, v138
	v_sub_f32_e32 v138, v139, v176
	v_fmac_f32_e32 v176, v105, v138
	v_lshlrev_b32_e32 v177, 16, v147
	v_lshlrev_b32_e32 v142, 16, v153
	v_mul_f32_e32 v138, v109, v176
	v_fmac_f32_e32 v135, v138, v138
	v_sub_f32_e32 v138, v142, v177
	v_fmac_f32_e32 v177, v106, v138
	v_and_b32_e32 v174, 0xffff0000, v147
	v_and_b32_e32 v143, 0xffff0000, v153
	v_mul_f32_e32 v138, v110, v177
	v_fmac_f32_e32 v135, v138, v138
	v_sub_f32_e32 v138, v143, v174
	v_fmac_f32_e32 v174, v107, v138
	v_mul_f32_e32 v138, v111, v174
	v_fmac_f32_e32 v135, v138, v138
	s_waitcnt vmcnt(0)
	v_lshlrev_b32_e32 v171, 16, v148
	v_lshlrev_b32_e32 v138, 16, v140
	v_sub_f32_e32 v138, v138, v171
	v_fmac_f32_e32 v171, v96, v138
	v_and_b32_e32 v172, 0xffff0000, v148
	v_and_b32_e32 v139, 0xffff0000, v140
	v_mul_f32_e32 v138, v100, v171
	v_fmac_f32_e32 v135, v138, v138
	v_sub_f32_e32 v138, v139, v172
	v_fmac_f32_e32 v172, v97, v138
	v_lshlrev_b32_e32 v173, 16, v149
	v_lshlrev_b32_e32 v140, 16, v141
	v_mul_f32_e32 v138, v101, v172
	v_fmac_f32_e32 v135, v138, v138
	v_sub_f32_e32 v138, v140, v173
	v_fmac_f32_e32 v173, v98, v138
	v_and_b32_e32 v168, 0xffff0000, v149
	v_and_b32_e32 v141, 0xffff0000, v141
	v_mul_f32_e32 v138, v102, v173
	v_fmac_f32_e32 v135, v138, v138
	v_sub_f32_e32 v138, v141, v168
	v_fmac_f32_e32 v168, v99, v138
	v_mul_f32_e32 v138, v103, v168
	v_add_u32_e32 v192, 0xe000, v192
	v_fmac_f32_e32 v135, v138, v138
	v_lshl_add_u64 v[138:139], v[192:193], 1, s[16:17]
	v_lshl_add_u64 v[140:141], v[132:133], 1, v[138:139]
	s_movk_i32 s33, 0xf000
	v_add_co_u32_e32 v138, vcc, s33, v140
	global_load_dwordx2 v[142:143], v[140:141], off offset:2592
	s_nop 0
	v_addc_co_u32_e32 v139, vcc, -1, v141, vcc
	global_load_dwordx2 v[144:145], v[138:139], off offset:-480
	global_load_dwordx2 v[224:225], v[140:141], off offset:2624
	global_load_dwordx2 v[226:227], v[138:139], off offset:-448
	global_load_dwordx2 v[228:229], v[140:141], off offset:2656
	global_load_dwordx2 v[230:231], v[138:139], off offset:-416
	global_load_dwordx2 v[246:247], v[140:141], off offset:2688
	global_load_dwordx2 v[248:249], v[138:139], off offset:-384
	s_waitcnt lgkmcnt(0)
	s_add_u32 s4, s4, s44
	s_addc_u32 s5, s5, s45
	s_add_u32 s2, s2, s44
	s_addc_u32 s3, s3, s45
	s_add_u32 s0, s0, s44
	s_addc_u32 s1, s1, s45
	s_waitcnt vmcnt(1)
	v_lshlrev_b32_e32 v167, 16, v142
	v_and_b32_e32 v169, 0xffff0000, v142
	v_lshlrev_b32_e32 v170, 16, v143
	s_waitcnt vmcnt(0)
; DI void rwkv_prep_item(KA a, const int l, LAS unsigned char* lds, const int tile) {
;     ...
;         for (int ct = 0; ct < 4; ++ct) { const int c4 = hd * 64 + ct * 16 + 4 * fq; const f32x4 muk = *(const f32x4*)(mu + 256 + c4), kk4 = *(const f32x4*)(kkw + c4);
;             const bf16* hp = H + (size_t)tk * HP + C_RK + c4; const v2u cu = *(const v2u*)hp; v2u pv = {0u, 0u}; if (!first) pv = *(const v2u*)(hp - HP);
;             const float c_[4] = {bflo(cu.x), bfhi(cu.x), bflo(cu.y), bfhi(cu.y)}, p_[4] = {bflo(pv.x), bfhi(pv.x), bflo(pv.y), bfhi(pv.y)};
; #pragma unroll
;             for (int j = 0; j < 4; ++j) { const float k = c_[j] + (p_[j] - c_[j]) * muk[j]; kx[rt][ct][j] = k; const float kk = k * kk4[j]; ss[rt] += kk * kk; } } }
; #pragma unroll
;     for (int rt = 0; rt < 2; ++rt) { float s_ = ss[rt]; s_ += __shfl_xor(s_, 16); s_ += __shfl_xor(s_, 32); ss[rt] = 1.f / fmaxf(sqrtf(s_), 1e-12f); }
;     float* Rw = (float*)(ws + WS_RW); bf16* Rr = (bf16*)(ws + WS_RR); bf16* Rk = (bf16*)(ws + WS_RK); bf16* Rv = (bf16*)(ws + WS_RV); bf16* Ra = (bf16*)(ws + WS_RA); bf16* Rb = (bf16*)(ws + WS_RB); bf16* VF = (bf16*)(ws + WS_VF);
; #pragma unroll
;     for (int rt = 0; rt < 2; ++rt) { const int tk = t0 + 32 * th + 16 * rt + fr; const bool first = (tk & (SEQ - 1)) == 0;
; #pragma unroll
;         for (int ct = 0; ct < 4; ++ct) { const int c4 = hd * 64 + ct * 16 + 4 * fq; const size_t ro = (size_t)tk * 256 + c4;
;             const f32x4 mur = *(const f32x4*)(mu + c4), muv4 = *(const f32x4*)(mu + 512 + c4), w04 = *(const f32x4*)(w0 + c4), a04 = *(const f32x4*)(a0 + c4), kk4 = *(const f32x4*)(kkw + c4), ka4 = *(const f32x4*)(kaw + c4);
	v_lshlrev_b32_e32 v142, 16, v144
	v_sub_f32_e32 v142, v142, v167
	v_and_b32_e32 v166, 0xffff0000, v143
	v_and_b32_e32 v143, 0xffff0000, v144
	v_fmac_f32_e32 v167, v120, v142
	v_mul_f32_e32 v120, v124, v167
	v_sub_f32_e32 v124, v143, v169
	v_fmac_f32_e32 v169, v121, v124
	v_lshlrev_b32_e32 v144, 16, v145
	v_mul_f32_e32 v120, v120, v120
	v_mul_f32_e32 v121, v125, v169
	v_fmac_f32_e32 v120, v121, v121
	v_sub_f32_e32 v121, v144, v170
	v_fmac_f32_e32 v170, v122, v121
	v_and_b32_e32 v145, 0xffff0000, v145
	v_mul_f32_e32 v121, v126, v170
	v_fmac_f32_e32 v120, v121, v121
	v_sub_f32_e32 v121, v145, v166
	v_fmac_f32_e32 v166, v123, v121
	v_mul_f32_e32 v121, v127, v166
	v_fmac_f32_e32 v120, v121, v121
	s_waitcnt vmcnt(1)
	v_lshlrev_b32_e32 v163, 16, v224
	s_waitcnt vmcnt(0)
	v_lshlrev_b32_e32 v121, 16, v226
	v_sub_f32_e32 v121, v121, v163
	v_fmac_f32_e32 v163, v112, v121
	v_and_b32_e32 v164, 0xffff0000, v224
	v_and_b32_e32 v122, 0xffff0000, v226
	v_mul_f32_e32 v112, v116, v163
	v_fmac_f32_e32 v120, v112, v112
	v_sub_f32_e32 v112, v122, v164
	v_fmac_f32_e32 v164, v113, v112
	v_lshlrev_b32_e32 v165, 16, v225
	v_and_b32_e32 v161, 0xffff0000, v225
	v_lshlrev_b32_e32 v123, 16, v227
	v_mul_f32_e32 v112, v117, v164
	v_fmac_f32_e32 v120, v112, v112
	v_sub_f32_e32 v112, v123, v165
	v_fmac_f32_e32 v165, v114, v112
	v_and_b32_e32 v124, 0xffff0000, v227
	v_mul_f32_e32 v112, v118, v165
	v_fmac_f32_e32 v120, v112, v112
	v_sub_f32_e32 v112, v124, v161
	v_fmac_f32_e32 v161, v115, v112
	v_mul_f32_e32 v112, v119, v161
	v_fmac_f32_e32 v120, v112, v112
	v_lshl_add_u64 v[122:123], s[0:1], 0, v[136:137]
	v_lshl_add_u64 v[124:125], s[2:3], 0, v[136:137]
	v_mov_b32_e32 v116, 0
	v_mov_b32_e32 v117, 0
	v_mov_b32_e32 v118, 0
	v_mov_b32_e32 v119, 0
	s_waitcnt vmcnt(1)
	v_lshlrev_b32_e32 v159, 16, v228
	v_and_b32_e32 v160, 0xffff0000, v228
	s_waitcnt vmcnt(0)
	v_lshlrev_b32_e32 v112, 16, v230
	v_sub_f32_e32 v112, v112, v159
	v_fmac_f32_e32 v159, v104, v112
	v_lshlrev_b32_e32 v162, 16, v229
	v_and_b32_e32 v158, 0xffff0000, v229
	v_and_b32_e32 v113, 0xffff0000, v230
	v_mul_f32_e32 v104, v108, v159
	v_fmac_f32_e32 v120, v104, v104
	v_sub_f32_e32 v104, v113, v160
	v_fmac_f32_e32 v160, v105, v104
	v_lshlrev_b32_e32 v114, 16, v231
	v_mul_f32_e32 v104, v109, v160
	v_fmac_f32_e32 v120, v104, v104
	v_sub_f32_e32 v104, v114, v162
	v_fmac_f32_e32 v162, v106, v104
	v_and_b32_e32 v115, 0xffff0000, v231
	v_mul_f32_e32 v104, v110, v162
	v_fmac_f32_e32 v120, v104, v104
	v_sub_f32_e32 v104, v115, v158
	v_fmac_f32_e32 v158, v107, v104
	v_mul_f32_e32 v104, v111, v158
	v_fmac_f32_e32 v120, v104, v104
	v_mov_b32_e32 v140, 0
	s_waitcnt vmcnt(1)
	v_lshlrev_b32_e32 v155, 16, v246
	v_and_b32_e32 v156, 0xffff0000, v246
	s_waitcnt vmcnt(0)
	v_lshlrev_b32_e32 v104, 16, v248
	v_sub_f32_e32 v104, v104, v155
	v_fmac_f32_e32 v155, v96, v104
	v_lshlrev_b32_e32 v157, 16, v247
	v_and_b32_e32 v154, 0xffff0000, v247
	v_and_b32_e32 v105, 0xffff0000, v248
	v_mul_f32_e32 v96, v100, v155
	v_fmac_f32_e32 v120, v96, v96
	v_sub_f32_e32 v96, v105, v156
	v_fmac_f32_e32 v156, v97, v96
	v_lshlrev_b32_e32 v106, 16, v249
	v_mul_f32_e32 v96, v101, v156
	v_fmac_f32_e32 v120, v96, v96
	v_sub_f32_e32 v96, v106, v157
	v_fmac_f32_e32 v157, v98, v96
	v_and_b32_e32 v107, 0xffff0000, v249
	v_mul_f32_e32 v96, v102, v157
	v_fmac_f32_e32 v120, v96, v96
	v_sub_f32_e32 v96, v107, v154
	v_fmac_f32_e32 v154, v99, v96
	v_mul_f32_e32 v96, v103, v154
	v_and_b32_e32 v97, 64, v238
	v_fmac_f32_e32 v120, v96, v96
	v_xor_b32_e32 v96, 16, v238
	v_add_u32_e32 v97, 64, v97
	v_cmp_lt_i32_e32 vcc, v96, v97
	v_xor_b32_e32 v98, 32, v238
	global_load_dwordx4 v[100:103], v[130:131], off
	global_load_dwordx4 v[112:115], v[130:131], off offset:2048
	v_cndmask_b32_e32 v96, v238, v96, vcc
	v_lshlrev_b32_e32 v96, 2, v96
	v_cmp_lt_i32_e32 vcc, v98, v97
	global_load_dwordx4 v[104:107], v[122:123], off
	s_load_dwordx2 s[0:1], s[12:13], 0x68
	v_cndmask_b32_e32 v97, v238, v98, vcc
	ds_bpermute_b32 v98, v96, v135
	ds_bpermute_b32 v96, v96, v120
	v_lshlrev_b32_e32 v97, 2, v97
	s_and_b64 vcc, exec, s[40:41]
	s_waitcnt lgkmcnt(0)
	v_lshl_add_u64 v[126:127], v[132:133], 2, s[0:1]
	v_add_f32_e32 v192, v135, v98
	v_add_f32_e32 v189, v120, v96
	v_lshl_add_u64 v[120:121], s[4:5], 0, v[136:137]
	ds_bpermute_b32 v206, v97, v192
	ds_bpermute_b32 v190, v97, v189
	global_load_dwordx4 v[108:111], v[120:121], off
	global_load_dwordx4 v[96:99], v[124:125], off
	s_cbranch_vccnz .LBB0_350
	global_load_dwordx4 v[116:119], v[126:127], off
